# GEMM main loops: the two k-chunk MFMAs of each accumulator issued back to back (SrcC forwarding), accumulators visited in serpentine operand order; per-accumulator summation order unchanged (bit-ident
# speedup vs baseline: 1.0142x; 1.0010x over previous
.LBB0_202:
	ds_read_b128 v[112:115], v218
	ds_read_b128 v[116:119], v218 offset:1024
	ds_read_b128 v[120:123], v218 offset:2048
	ds_read_b128 v[124:127], v218 offset:3072
	s_waitcnt vmcnt(0)
	ds_read_b128 v[128:131], v219
	ds_read_b128 v[132:135], v219 offset:1024
	ds_read_b128 v[136:139], v219 offset:2048
	ds_read_b128 v[140:143], v219 offset:3072
	s_add_u32 s69, s12, 0xfffc0080
	s_addc_u32 s73, s13, -1
	s_cmp_eq_u32 s68, 12
	s_cselect_b32 s83, s1, s73
	s_cselect_b32 s82, s2, s69
	s_cselect_b32 s81, s3, s66
	s_cselect_b32 s80, s34, s35
	v_lshl_add_u64 v[230:231], s[12:13], 0, v[192:193]
	s_add_i32 m0, s15, 0xc000
	ds_read_b128 v[152:155], v220
	ds_read_b128 v[156:159], v220 offset:1024
	ds_read_b128 v[160:163], v220 offset:2048
	ds_read_b128 v[164:167], v220 offset:3072
	ds_read_b128 v[200:203], v220 offset:4096
	ds_read_b128 v[204:207], v220 offset:5120
	ds_read_b128 v[208:211], v220 offset:6144
	ds_read_b128 v[226:229], v220 offset:7168
	global_load_lds_dwordx4 v[230:231], off
	v_lshl_add_u64 v[230:231], s[12:13], 0, v[194:195]
	s_add_i32 m0, s15, 0xe000
	s_nop 0
	global_load_lds_dwordx4 v[230:231], off
	s_waitcnt vmcnt(8)
	s_waitcnt lgkmcnt(0)
	s_barrier
	s_setprio 1
	s_waitcnt lgkmcnt(0)
	v_mfma_f32_16x16x32_bf16 v[172:175], v[112:115], v[152:155], v[172:175]
	v_mfma_f32_16x16x32_bf16 v[172:175], v[116:119], v[156:159], v[172:175]
	v_mfma_f32_16x16x32_bf16 v[168:171], v[120:123], v[152:155], v[168:171]
	v_mfma_f32_16x16x32_bf16 v[168:171], v[124:127], v[156:159], v[168:171]
	v_mfma_f32_16x16x32_bf16 v[104:107], v[120:123], v[160:163], v[104:107]
	v_mfma_f32_16x16x32_bf16 v[104:107], v[124:127], v[164:167], v[104:107]
	v_mfma_f32_16x16x32_bf16 v[108:111], v[112:115], v[160:163], v[108:111]
	v_mfma_f32_16x16x32_bf16 v[108:111], v[116:119], v[164:167], v[108:111]
	v_mfma_f32_16x16x32_bf16 v[92:95], v[112:115], v[200:203], v[92:95]
	v_mfma_f32_16x16x32_bf16 v[92:95], v[116:119], v[204:207], v[92:95]
	v_mfma_f32_16x16x32_bf16 v[88:91], v[120:123], v[200:203], v[88:91]
	v_mfma_f32_16x16x32_bf16 v[88:91], v[124:127], v[204:207], v[88:91]
	v_mfma_f32_16x16x32_bf16 v[72:75], v[120:123], v[208:211], v[72:75]
	v_mfma_f32_16x16x32_bf16 v[72:75], v[124:127], v[226:229], v[72:75]
	v_mfma_f32_16x16x32_bf16 v[76:79], v[112:115], v[208:211], v[76:79]
	v_mfma_f32_16x16x32_bf16 v[76:79], v[116:119], v[226:229], v[76:79]
	s_setprio 0
	s_setprio 1
	v_mfma_f32_16x16x32_bf16 v[148:151], v[128:131], v[152:155], v[148:151]
	v_mfma_f32_16x16x32_bf16 v[148:151], v[132:135], v[156:159], v[148:151]
	v_mfma_f32_16x16x32_bf16 v[144:147], v[136:139], v[152:155], v[144:147]
	v_mfma_f32_16x16x32_bf16 v[144:147], v[140:143], v[156:159], v[144:147]
	v_mfma_f32_16x16x32_bf16 v[96:99], v[136:139], v[160:163], v[96:99]
	v_mfma_f32_16x16x32_bf16 v[96:99], v[140:143], v[164:167], v[96:99]
	v_mfma_f32_16x16x32_bf16 v[100:103], v[128:131], v[160:163], v[100:103]
	v_mfma_f32_16x16x32_bf16 v[100:103], v[132:135], v[164:167], v[100:103]
	v_mfma_f32_16x16x32_bf16 v[84:87], v[128:131], v[200:203], v[84:87]
	v_mfma_f32_16x16x32_bf16 v[84:87], v[132:135], v[204:207], v[84:87]
	v_mfma_f32_16x16x32_bf16 v[80:83], v[136:139], v[200:203], v[80:83]
	v_mfma_f32_16x16x32_bf16 v[80:83], v[140:143], v[204:207], v[80:83]
	v_mfma_f32_16x16x32_bf16 v[64:67], v[136:139], v[208:211], v[64:67]
	v_mfma_f32_16x16x32_bf16 v[64:67], v[140:143], v[226:229], v[64:67]
	v_mfma_f32_16x16x32_bf16 v[68:71], v[128:131], v[208:211], v[68:71]
	v_mfma_f32_16x16x32_bf16 v[68:71], v[132:135], v[226:229], v[68:71]
	s_setprio 0
	s_barrier
	s_add_i32 s69, s59, s14
	v_lshl_add_u64 v[230:231], s[80:81], 0, v[178:179]
	s_mov_b32 m0, s69
	ds_read_b128 v[152:155], v220 offset:16384
	ds_read_b128 v[156:159], v220 offset:17408
	ds_read_b128 v[160:163], v220 offset:18432
	ds_read_b128 v[164:167], v220 offset:19456
	ds_read_b128 v[200:203], v220 offset:20480
	ds_read_b128 v[204:207], v220 offset:21504
	ds_read_b128 v[208:211], v220 offset:22528
	ds_read_b128 v[226:229], v220 offset:23552
	global_load_lds_dwordx4 v[230:231], off
	s_add_i32 m0, s69, 0x2000
	s_add_u32 s86, s80, 0x40000
	v_lshl_add_u64 v[232:233], s[80:81], 0, v[182:183]
	s_addc_u32 s87, s81, 0
	s_add_i32 s69, s65, s14
	global_load_lds_dwordx4 v[232:233], off
	v_lshl_add_u64 v[234:235], s[86:87], 0, v[178:179]
	s_mov_b32 m0, s69
	v_lshl_add_u64 v[236:237], s[82:83], 0, v[180:181]
	global_load_lds_dwordx4 v[234:235], off
	v_lshl_add_u64 v[234:235], s[86:87], 0, v[182:183]
	s_add_i32 m0, s69, 0x2000
	s_nop 0
	global_load_lds_dwordx4 v[234:235], off
	v_lshl_add_u64 v[234:235], s[82:83], 0, v[176:177]
	s_mov_b32 m0, s15
	s_nop 0
	global_load_lds_dwordx4 v[234:235], off
	s_mov_b32 m0, s52
	s_nop 0
	global_load_lds_dwordx4 v[236:237], off
	s_waitcnt vmcnt(8)
	s_waitcnt lgkmcnt(0)
	s_barrier
	s_setprio 1
	s_waitcnt lgkmcnt(0)
	v_mfma_f32_16x16x32_bf16 v[60:63], v[112:115], v[152:155], v[60:63]
	v_mfma_f32_16x16x32_bf16 v[60:63], v[116:119], v[156:159], v[60:63]
	v_mfma_f32_16x16x32_bf16 v[56:59], v[120:123], v[152:155], v[56:59]
	v_mfma_f32_16x16x32_bf16 v[56:59], v[124:127], v[156:159], v[56:59]
	v_mfma_f32_16x16x32_bf16 v[40:43], v[120:123], v[160:163], v[40:43]
	v_mfma_f32_16x16x32_bf16 v[40:43], v[124:127], v[164:167], v[40:43]
	v_mfma_f32_16x16x32_bf16 v[44:47], v[112:115], v[160:163], v[44:47]
	v_mfma_f32_16x16x32_bf16 v[44:47], v[116:119], v[164:167], v[44:47]
	v_mfma_f32_16x16x32_bf16 v[28:31], v[112:115], v[200:203], v[28:31]
	v_mfma_f32_16x16x32_bf16 v[28:31], v[116:119], v[204:207], v[28:31]
	v_mfma_f32_16x16x32_bf16 v[24:27], v[120:123], v[200:203], v[24:27]
	v_mfma_f32_16x16x32_bf16 v[24:27], v[124:127], v[204:207], v[24:27]
	v_mfma_f32_16x16x32_bf16 v[8:11], v[120:123], v[208:211], v[8:11]
	v_mfma_f32_16x16x32_bf16 v[8:11], v[124:127], v[226:229], v[8:11]
	v_mfma_f32_16x16x32_bf16 v[12:15], v[112:115], v[208:211], v[12:15]
	v_mfma_f32_16x16x32_bf16 v[12:15], v[116:119], v[226:229], v[12:15]
	s_setprio 0
	s_setprio 1
	v_mfma_f32_16x16x32_bf16 v[52:55], v[128:131], v[152:155], v[52:55]
	v_mfma_f32_16x16x32_bf16 v[52:55], v[132:135], v[156:159], v[52:55]
	v_mfma_f32_16x16x32_bf16 v[48:51], v[136:139], v[152:155], v[48:51]
	v_mfma_f32_16x16x32_bf16 v[48:51], v[140:143], v[156:159], v[48:51]
	v_mfma_f32_16x16x32_bf16 v[32:35], v[136:139], v[160:163], v[32:35]
	v_mfma_f32_16x16x32_bf16 v[32:35], v[140:143], v[164:167], v[32:35]
	v_mfma_f32_16x16x32_bf16 v[36:39], v[128:131], v[160:163], v[36:39]
	v_mfma_f32_16x16x32_bf16 v[36:39], v[132:135], v[164:167], v[36:39]
	v_mfma_f32_16x16x32_bf16 v[20:23], v[128:131], v[200:203], v[20:23]
	v_mfma_f32_16x16x32_bf16 v[20:23], v[132:135], v[204:207], v[20:23]
	v_mfma_f32_16x16x32_bf16 v[16:19], v[136:139], v[200:203], v[16:19]
	v_mfma_f32_16x16x32_bf16 v[16:19], v[140:143], v[204:207], v[16:19]
	v_mfma_f32_16x16x32_bf16 v[0:3], v[136:139], v[208:211], v[0:3]
	v_mfma_f32_16x16x32_bf16 v[0:3], v[140:143], v[226:229], v[0:3]
	v_mfma_f32_16x16x32_bf16 v[4:7], v[128:131], v[208:211], v[4:7]
	v_mfma_f32_16x16x32_bf16 v[4:7], v[132:135], v[226:229], v[4:7]
	s_setprio 0
	s_barrier
	s_add_i32 s69, 0, 0x18000
	s_add_i32 s73, 0, 0x1c000
	v_add_u32_e32 v124, s69, v212
	v_add_u32_e32 v140, s73, v212
	ds_read_b128 v[112:115], v124
	ds_read_b128 v[116:119], v124 offset:1024
	ds_read_b128 v[120:123], v124 offset:2048
	ds_read_b128 v[124:127], v124 offset:3072
	ds_read_b128 v[128:131], v140
	ds_read_b128 v[132:135], v140 offset:1024
	ds_read_b128 v[136:139], v140 offset:2048
	ds_read_b128 v[140:143], v140 offset:3072
	s_add_u32 s82, s82, 0x40000
	s_addc_u32 s83, s83, 0
	s_mov_b32 m0, s53
	v_lshl_add_u64 v[238:239], s[82:83], 0, v[176:177]
	ds_read_b128 v[152:155], v220 offset:32768
	ds_read_b128 v[156:159], v220 offset:33792
	ds_read_b128 v[160:163], v220 offset:34816
	ds_read_b128 v[164:167], v220 offset:35840
	ds_read_b128 v[200:203], v220 offset:36864
	ds_read_b128 v[204:207], v220 offset:37888
	ds_read_b128 v[208:211], v220 offset:38912
	ds_read_b128 v[226:229], v220 offset:39936
	global_load_lds_dwordx4 v[238:239], off
	v_lshl_add_u64 v[238:239], s[82:83], 0, v[180:181]
	s_mov_b32 m0, s54
	s_nop 0
	global_load_lds_dwordx4 v[238:239], off
	s_waitcnt vmcnt(8)
	s_waitcnt lgkmcnt(0)
	s_barrier
	s_setprio 1
	s_waitcnt lgkmcnt(0)
	v_mfma_f32_16x16x32_bf16 v[172:175], v[112:115], v[152:155], v[172:175]
	v_mfma_f32_16x16x32_bf16 v[172:175], v[116:119], v[156:159], v[172:175]
	v_mfma_f32_16x16x32_bf16 v[168:171], v[120:123], v[152:155], v[168:171]
	v_mfma_f32_16x16x32_bf16 v[168:171], v[124:127], v[156:159], v[168:171]
	v_mfma_f32_16x16x32_bf16 v[104:107], v[120:123], v[160:163], v[104:107]
	v_mfma_f32_16x16x32_bf16 v[104:107], v[124:127], v[164:167], v[104:107]
	v_mfma_f32_16x16x32_bf16 v[108:111], v[112:115], v[160:163], v[108:111]
	v_mfma_f32_16x16x32_bf16 v[108:111], v[116:119], v[164:167], v[108:111]
	v_mfma_f32_16x16x32_bf16 v[92:95], v[112:115], v[200:203], v[92:95]
	v_mfma_f32_16x16x32_bf16 v[92:95], v[116:119], v[204:207], v[92:95]
	v_mfma_f32_16x16x32_bf16 v[88:91], v[120:123], v[200:203], v[88:91]
	v_mfma_f32_16x16x32_bf16 v[88:91], v[124:127], v[204:207], v[88:91]
	v_mfma_f32_16x16x32_bf16 v[72:75], v[120:123], v[208:211], v[72:75]
	v_mfma_f32_16x16x32_bf16 v[72:75], v[124:127], v[226:229], v[72:75]
	v_mfma_f32_16x16x32_bf16 v[76:79], v[112:115], v[208:211], v[76:79]
	v_mfma_f32_16x16x32_bf16 v[76:79], v[116:119], v[226:229], v[76:79]
	s_setprio 0
	s_setprio 1
	v_mfma_f32_16x16x32_bf16 v[148:151], v[128:131], v[152:155], v[148:151]
	v_mfma_f32_16x16x32_bf16 v[148:151], v[132:135], v[156:159], v[148:151]
	v_mfma_f32_16x16x32_bf16 v[144:147], v[136:139], v[152:155], v[144:147]
	v_mfma_f32_16x16x32_bf16 v[144:147], v[140:143], v[156:159], v[144:147]
	v_mfma_f32_16x16x32_bf16 v[96:99], v[136:139], v[160:163], v[96:99]
	v_mfma_f32_16x16x32_bf16 v[96:99], v[140:143], v[164:167], v[96:99]
	v_mfma_f32_16x16x32_bf16 v[100:103], v[128:131], v[160:163], v[100:103]
	v_mfma_f32_16x16x32_bf16 v[100:103], v[132:135], v[164:167], v[100:103]
	v_mfma_f32_16x16x32_bf16 v[84:87], v[128:131], v[200:203], v[84:87]
	v_mfma_f32_16x16x32_bf16 v[84:87], v[132:135], v[204:207], v[84:87]
	v_mfma_f32_16x16x32_bf16 v[80:83], v[136:139], v[200:203], v[80:83]
	v_mfma_f32_16x16x32_bf16 v[80:83], v[140:143], v[204:207], v[80:83]
	v_mfma_f32_16x16x32_bf16 v[64:67], v[136:139], v[208:211], v[64:67]
	v_mfma_f32_16x16x32_bf16 v[64:67], v[140:143], v[226:229], v[64:67]
	v_mfma_f32_16x16x32_bf16 v[68:71], v[128:131], v[208:211], v[68:71]
	v_mfma_f32_16x16x32_bf16 v[68:71], v[132:135], v[226:229], v[68:71]
	s_setprio 0
	s_barrier
	s_add_i32 s69, s69, s14
	v_lshl_add_u64 v[230:231], v[230:231], 0, s[40:41]
	s_mov_b32 m0, s69
	ds_read_b128 v[152:155], v220 offset:49152
	ds_read_b128 v[156:159], v220 offset:50176
	ds_read_b128 v[160:163], v220 offset:51200
	ds_read_b128 v[164:167], v220 offset:52224
	ds_read_b128 v[200:203], v220 offset:53248
	ds_read_b128 v[204:207], v220 offset:54272
	ds_read_b128 v[208:211], v220 offset:55296
	ds_read_b128 v[226:229], v220 offset:56320
	global_load_lds_dwordx4 v[230:231], off
	s_add_i32 m0, s69, 0x2000
	s_add_u32 s80, s80, 0x40080
	v_lshl_add_u64 v[230:231], v[232:233], 0, s[40:41]
	s_addc_u32 s81, s81, 0
	s_add_i32 s69, s73, s14
	global_load_lds_dwordx4 v[230:231], off
	v_lshl_add_u64 v[230:231], s[80:81], 0, v[178:179]
	s_mov_b32 m0, s69
	s_nop 0
	global_load_lds_dwordx4 v[230:231], off
	v_lshl_add_u64 v[230:231], s[80:81], 0, v[182:183]
	s_add_i32 m0, s69, 0x2000
	s_nop 0
	global_load_lds_dwordx4 v[230:231], off
	v_lshl_add_u64 v[230:231], v[234:235], 0, s[40:41]
	s_mov_b32 m0, s57
	s_nop 0
	global_load_lds_dwordx4 v[230:231], off
	v_lshl_add_u64 v[230:231], v[236:237], 0, s[40:41]
	s_mov_b32 m0, s58
	s_nop 0
	global_load_lds_dwordx4 v[230:231], off
	s_waitcnt vmcnt(8)
	s_waitcnt lgkmcnt(0)
	s_barrier
	s_setprio 1
	s_waitcnt lgkmcnt(0)
	v_mfma_f32_16x16x32_bf16 v[60:63], v[112:115], v[152:155], v[60:63]
	v_mfma_f32_16x16x32_bf16 v[60:63], v[116:119], v[156:159], v[60:63]
	v_mfma_f32_16x16x32_bf16 v[56:59], v[120:123], v[152:155], v[56:59]
	v_mfma_f32_16x16x32_bf16 v[56:59], v[124:127], v[156:159], v[56:59]
	v_mfma_f32_16x16x32_bf16 v[40:43], v[120:123], v[160:163], v[40:43]
	v_mfma_f32_16x16x32_bf16 v[40:43], v[124:127], v[164:167], v[40:43]
	v_mfma_f32_16x16x32_bf16 v[44:47], v[112:115], v[160:163], v[44:47]
	v_mfma_f32_16x16x32_bf16 v[44:47], v[116:119], v[164:167], v[44:47]
	v_mfma_f32_16x16x32_bf16 v[28:31], v[112:115], v[200:203], v[28:31]
	v_mfma_f32_16x16x32_bf16 v[28:31], v[116:119], v[204:207], v[28:31]
	v_mfma_f32_16x16x32_bf16 v[24:27], v[120:123], v[200:203], v[24:27]
	v_mfma_f32_16x16x32_bf16 v[24:27], v[124:127], v[204:207], v[24:27]
	v_mfma_f32_16x16x32_bf16 v[8:11], v[120:123], v[208:211], v[8:11]
	v_mfma_f32_16x16x32_bf16 v[8:11], v[124:127], v[226:229], v[8:11]
	v_mfma_f32_16x16x32_bf16 v[12:15], v[112:115], v[208:211], v[12:15]
	v_mfma_f32_16x16x32_bf16 v[12:15], v[116:119], v[226:229], v[12:15]
	s_setprio 0
	s_setprio 1
	v_mfma_f32_16x16x32_bf16 v[52:55], v[128:131], v[152:155], v[52:55]
	v_mfma_f32_16x16x32_bf16 v[52:55], v[132:135], v[156:159], v[52:55]
	v_mfma_f32_16x16x32_bf16 v[48:51], v[136:139], v[152:155], v[48:51]
	v_mfma_f32_16x16x32_bf16 v[48:51], v[140:143], v[156:159], v[48:51]
	v_mfma_f32_16x16x32_bf16 v[32:35], v[136:139], v[160:163], v[32:35]
	v_mfma_f32_16x16x32_bf16 v[32:35], v[140:143], v[164:167], v[32:35]
	v_mfma_f32_16x16x32_bf16 v[36:39], v[128:131], v[160:163], v[36:39]
	v_mfma_f32_16x16x32_bf16 v[36:39], v[132:135], v[164:167], v[36:39]
	v_mfma_f32_16x16x32_bf16 v[20:23], v[128:131], v[200:203], v[20:23]
	v_mfma_f32_16x16x32_bf16 v[20:23], v[132:135], v[204:207], v[20:23]
	v_mfma_f32_16x16x32_bf16 v[16:19], v[136:139], v[200:203], v[16:19]
	v_mfma_f32_16x16x32_bf16 v[16:19], v[140:143], v[204:207], v[16:19]
	v_mfma_f32_16x16x32_bf16 v[0:3], v[136:139], v[208:211], v[0:3]
	v_mfma_f32_16x16x32_bf16 v[0:3], v[140:143], v[226:229], v[0:3]
	v_mfma_f32_16x16x32_bf16 v[4:7], v[128:131], v[208:211], v[4:7]
	v_mfma_f32_16x16x32_bf16 v[4:7], v[132:135], v[226:229], v[4:7]
	s_setprio 0
	s_barrier
	s_add_i32 s68, s68, 2
	s_add_u32 s12, s12, 0x100
	s_addc_u32 s13, s13, 0
	s_add_u32 s35, s35, 0x100
	s_addc_u32 s66, s66, 0
	s_cmp_gt_u32 s68, 13
	s_cbranch_scc0 .LBB0_202
	s_and_b64 vcc, exec, s[42:43]
	s_cbranch_vccz .LBB0_205
	s_barrier

.LBB0_646:
	ds_read_b128 v[88:91], v236
	ds_read_b128 v[100:103], v236 offset:1024
	ds_read_b128 v[112:115], v236 offset:2048
	ds_read_b128 v[124:127], v236 offset:3072
	ds_read_b128 v[136:139], v237
	ds_read_b128 v[148:151], v237 offset:1024
	ds_read_b128 v[152:155], v237 offset:2048
	ds_read_b128 v[156:159], v237 offset:3072
	s_add_u32 s44, s42, 0xfffc0080
	s_addc_u32 s45, s43, -1
	s_cmp_eq_u32 s57, 12
	s_cselect_b32 s47, s31, s45
	s_cselect_b32 s46, s41, s44
	s_cselect_b32 s45, s29, s56
	s_cselect_b32 s44, s54, s55
	v_lshl_add_u64 v[208:209], s[42:43], 0, v[194:195]
	s_add_i32 m0, s3, 0xc000
	ds_read_b128 v[160:163], v238
	ds_read_b128 v[164:167], v238 offset:1024
	ds_read_b128 v[168:171], v238 offset:2048
	ds_read_b128 v[172:175], v238 offset:3072
	ds_read_b128 v[176:179], v238 offset:4096
	ds_read_b128 v[180:183], v238 offset:5120
	ds_read_b128 v[202:205], v238 offset:6144
	ds_read_b128 v[228:231], v238 offset:7168
	global_load_lds_dwordx4 v[208:209], off
	v_lshl_add_u64 v[208:209], s[42:43], 0, v[196:197]
	s_add_i32 m0, s3, 0xe000
	s_nop 0
	global_load_lds_dwordx4 v[208:209], off
	s_waitcnt vmcnt(8)
	s_waitcnt lgkmcnt(0)
	s_barrier
	s_setprio 1
	s_waitcnt lgkmcnt(0)
	v_mfma_f32_16x16x32_bf16 v[144:147], v[88:91], v[160:163], v[144:147]
	v_mfma_f32_16x16x32_bf16 v[144:147], v[100:103], v[164:167], v[144:147]
	v_mfma_f32_16x16x32_bf16 v[140:143], v[112:115], v[160:163], v[140:143]
	v_mfma_f32_16x16x32_bf16 v[140:143], v[124:127], v[164:167], v[140:143]
	v_mfma_f32_16x16x32_bf16 v[116:119], v[112:115], v[168:171], v[116:119]
	v_mfma_f32_16x16x32_bf16 v[116:119], v[124:127], v[172:175], v[116:119]
	v_mfma_f32_16x16x32_bf16 v[120:123], v[88:91], v[168:171], v[120:123]
	v_mfma_f32_16x16x32_bf16 v[120:123], v[100:103], v[172:175], v[120:123]
	v_mfma_f32_16x16x32_bf16 v[96:99], v[88:91], v[176:179], v[96:99]
	v_mfma_f32_16x16x32_bf16 v[96:99], v[100:103], v[180:183], v[96:99]
	v_mfma_f32_16x16x32_bf16 v[92:95], v[112:115], v[176:179], v[92:95]
	v_mfma_f32_16x16x32_bf16 v[92:95], v[124:127], v[180:183], v[92:95]
	v_mfma_f32_16x16x32_bf16 v[72:75], v[112:115], v[202:205], v[72:75]
	v_mfma_f32_16x16x32_bf16 v[72:75], v[124:127], v[228:231], v[72:75]
	v_mfma_f32_16x16x32_bf16 v[76:79], v[88:91], v[202:205], v[76:79]
	v_mfma_f32_16x16x32_bf16 v[76:79], v[100:103], v[228:231], v[76:79]
	s_setprio 0
	s_setprio 1
	v_mfma_f32_16x16x32_bf16 v[132:135], v[136:139], v[160:163], v[132:135]
	v_mfma_f32_16x16x32_bf16 v[132:135], v[148:151], v[164:167], v[132:135]
	v_mfma_f32_16x16x32_bf16 v[128:131], v[152:155], v[160:163], v[128:131]
	v_mfma_f32_16x16x32_bf16 v[128:131], v[156:159], v[164:167], v[128:131]
	v_mfma_f32_16x16x32_bf16 v[104:107], v[152:155], v[168:171], v[104:107]
	v_mfma_f32_16x16x32_bf16 v[104:107], v[156:159], v[172:175], v[104:107]
	v_mfma_f32_16x16x32_bf16 v[108:111], v[136:139], v[168:171], v[108:111]
	v_mfma_f32_16x16x32_bf16 v[108:111], v[148:151], v[172:175], v[108:111]
	v_mfma_f32_16x16x32_bf16 v[84:87], v[136:139], v[176:179], v[84:87]
	v_mfma_f32_16x16x32_bf16 v[84:87], v[148:151], v[180:183], v[84:87]
	v_mfma_f32_16x16x32_bf16 v[80:83], v[152:155], v[176:179], v[80:83]
	v_mfma_f32_16x16x32_bf16 v[80:83], v[156:159], v[180:183], v[80:83]
	v_mfma_f32_16x16x32_bf16 v[64:67], v[152:155], v[202:205], v[64:67]
	v_mfma_f32_16x16x32_bf16 v[64:67], v[156:159], v[228:231], v[64:67]
	v_mfma_f32_16x16x32_bf16 v[68:71], v[136:139], v[202:205], v[68:71]
	v_mfma_f32_16x16x32_bf16 v[68:71], v[148:151], v[228:231], v[68:71]
	s_setprio 0
	s_barrier
	s_add_i32 s58, s51, s2
	v_lshl_add_u64 v[208:209], s[44:45], 0, v[186:187]
	s_mov_b32 m0, s58
	ds_read_b128 v[160:163], v238 offset:16384
	ds_read_b128 v[164:167], v238 offset:17408
	ds_read_b128 v[168:171], v238 offset:18432
	ds_read_b128 v[172:175], v238 offset:19456
	ds_read_b128 v[176:179], v238 offset:20480
	ds_read_b128 v[180:183], v238 offset:21504
	ds_read_b128 v[202:205], v238 offset:22528
	ds_read_b128 v[228:231], v238 offset:23552
	global_load_lds_dwordx4 v[208:209], off
	s_add_i32 m0, s58, 0x2000
	s_add_u32 s58, s44, 0x40000
	v_lshl_add_u64 v[212:213], s[44:45], 0, v[190:191]
	s_addc_u32 s59, s45, 0
	s_add_i32 s64, s52, s2
	global_load_lds_dwordx4 v[212:213], off
	v_lshl_add_u64 v[216:217], s[58:59], 0, v[186:187]
	s_mov_b32 m0, s64
	v_lshl_add_u64 v[220:221], s[46:47], 0, v[188:189]
	global_load_lds_dwordx4 v[216:217], off
	v_lshl_add_u64 v[216:217], s[58:59], 0, v[190:191]
	s_add_i32 m0, s64, 0x2000
	s_nop 0
	global_load_lds_dwordx4 v[216:217], off
	v_lshl_add_u64 v[216:217], s[46:47], 0, v[184:185]
	s_mov_b32 m0, s3
	s_nop 0
	global_load_lds_dwordx4 v[216:217], off
	s_mov_b32 m0, s33
	s_nop 0
	global_load_lds_dwordx4 v[220:221], off
	s_waitcnt vmcnt(8)
	s_waitcnt lgkmcnt(0)
	s_barrier
	s_setprio 1
	s_waitcnt lgkmcnt(0)
	v_mfma_f32_16x16x32_bf16 v[60:63], v[88:91], v[160:163], v[60:63]
	v_mfma_f32_16x16x32_bf16 v[60:63], v[100:103], v[164:167], v[60:63]
	v_mfma_f32_16x16x32_bf16 v[56:59], v[112:115], v[160:163], v[56:59]
	v_mfma_f32_16x16x32_bf16 v[56:59], v[124:127], v[164:167], v[56:59]
	v_mfma_f32_16x16x32_bf16 v[40:43], v[112:115], v[168:171], v[40:43]
	v_mfma_f32_16x16x32_bf16 v[40:43], v[124:127], v[172:175], v[40:43]
	v_mfma_f32_16x16x32_bf16 v[44:47], v[88:91], v[168:171], v[44:47]
	v_mfma_f32_16x16x32_bf16 v[44:47], v[100:103], v[172:175], v[44:47]
	v_mfma_f32_16x16x32_bf16 v[28:31], v[88:91], v[176:179], v[28:31]
	v_mfma_f32_16x16x32_bf16 v[28:31], v[100:103], v[180:183], v[28:31]
	v_mfma_f32_16x16x32_bf16 v[24:27], v[112:115], v[176:179], v[24:27]
	v_mfma_f32_16x16x32_bf16 v[24:27], v[124:127], v[180:183], v[24:27]
	v_mfma_f32_16x16x32_bf16 v[8:11], v[112:115], v[202:205], v[8:11]
	v_mfma_f32_16x16x32_bf16 v[8:11], v[124:127], v[228:231], v[8:11]
	v_mfma_f32_16x16x32_bf16 v[12:15], v[88:91], v[202:205], v[12:15]
	v_mfma_f32_16x16x32_bf16 v[12:15], v[100:103], v[228:231], v[12:15]
	s_setprio 0
	s_setprio 1
	v_mfma_f32_16x16x32_bf16 v[52:55], v[136:139], v[160:163], v[52:55]
	v_mfma_f32_16x16x32_bf16 v[52:55], v[148:151], v[164:167], v[52:55]
	v_mfma_f32_16x16x32_bf16 v[48:51], v[152:155], v[160:163], v[48:51]
	v_mfma_f32_16x16x32_bf16 v[48:51], v[156:159], v[164:167], v[48:51]
	v_mfma_f32_16x16x32_bf16 v[32:35], v[152:155], v[168:171], v[32:35]
	v_mfma_f32_16x16x32_bf16 v[32:35], v[156:159], v[172:175], v[32:35]
	v_mfma_f32_16x16x32_bf16 v[36:39], v[136:139], v[168:171], v[36:39]
	v_mfma_f32_16x16x32_bf16 v[36:39], v[148:151], v[172:175], v[36:39]
	v_mfma_f32_16x16x32_bf16 v[20:23], v[136:139], v[176:179], v[20:23]
	v_mfma_f32_16x16x32_bf16 v[20:23], v[148:151], v[180:183], v[20:23]
	v_mfma_f32_16x16x32_bf16 v[16:19], v[152:155], v[176:179], v[16:19]
	v_mfma_f32_16x16x32_bf16 v[16:19], v[156:159], v[180:183], v[16:19]
	v_mfma_f32_16x16x32_bf16 v[0:3], v[152:155], v[202:205], v[0:3]
	v_mfma_f32_16x16x32_bf16 v[0:3], v[156:159], v[228:231], v[0:3]
	v_mfma_f32_16x16x32_bf16 v[4:7], v[136:139], v[202:205], v[4:7]
	v_mfma_f32_16x16x32_bf16 v[4:7], v[148:151], v[228:231], v[4:7]
	s_setprio 0
	s_barrier
	s_add_i32 s58, 0, 0x18000
	s_add_i32 s59, 0, 0x1c000
	v_add_u32_e32 v124, s58, v211
	v_add_u32_e32 v156, s59, v211
	ds_read_b128 v[88:91], v124
	ds_read_b128 v[100:103], v124 offset:1024
	ds_read_b128 v[112:115], v124 offset:2048
	ds_read_b128 v[124:127], v124 offset:3072
	ds_read_b128 v[136:139], v156
	ds_read_b128 v[148:151], v156 offset:1024
	ds_read_b128 v[152:155], v156 offset:2048
	ds_read_b128 v[156:159], v156 offset:3072
	s_add_u32 s46, s46, 0x40000
	s_addc_u32 s47, s47, 0
	s_mov_b32 m0, s34
	v_lshl_add_u64 v[224:225], s[46:47], 0, v[184:185]
	ds_read_b128 v[160:163], v238 offset:32768
	ds_read_b128 v[164:167], v238 offset:33792
	ds_read_b128 v[168:171], v238 offset:34816
	ds_read_b128 v[172:175], v238 offset:35840
	ds_read_b128 v[176:179], v238 offset:36864
	ds_read_b128 v[180:183], v238 offset:37888
	ds_read_b128 v[202:205], v238 offset:38912
	ds_read_b128 v[228:231], v238 offset:39936
	global_load_lds_dwordx4 v[224:225], off
	v_lshl_add_u64 v[224:225], s[46:47], 0, v[188:189]
	s_mov_b32 m0, s35
	s_nop 0
	global_load_lds_dwordx4 v[224:225], off
	s_waitcnt vmcnt(8)
	s_waitcnt lgkmcnt(0)
	s_barrier
	s_setprio 1
	s_waitcnt lgkmcnt(0)
	v_mfma_f32_16x16x32_bf16 v[144:147], v[88:91], v[160:163], v[144:147]
	v_mfma_f32_16x16x32_bf16 v[144:147], v[100:103], v[164:167], v[144:147]
	v_mfma_f32_16x16x32_bf16 v[140:143], v[112:115], v[160:163], v[140:143]
	v_mfma_f32_16x16x32_bf16 v[140:143], v[124:127], v[164:167], v[140:143]
	v_mfma_f32_16x16x32_bf16 v[116:119], v[112:115], v[168:171], v[116:119]
	v_mfma_f32_16x16x32_bf16 v[116:119], v[124:127], v[172:175], v[116:119]
	v_mfma_f32_16x16x32_bf16 v[120:123], v[88:91], v[168:171], v[120:123]
	v_mfma_f32_16x16x32_bf16 v[120:123], v[100:103], v[172:175], v[120:123]
	v_mfma_f32_16x16x32_bf16 v[96:99], v[88:91], v[176:179], v[96:99]
	v_mfma_f32_16x16x32_bf16 v[96:99], v[100:103], v[180:183], v[96:99]
	v_mfma_f32_16x16x32_bf16 v[92:95], v[112:115], v[176:179], v[92:95]
	v_mfma_f32_16x16x32_bf16 v[92:95], v[124:127], v[180:183], v[92:95]
	v_mfma_f32_16x16x32_bf16 v[72:75], v[112:115], v[202:205], v[72:75]
	v_mfma_f32_16x16x32_bf16 v[72:75], v[124:127], v[228:231], v[72:75]
	v_mfma_f32_16x16x32_bf16 v[76:79], v[88:91], v[202:205], v[76:79]
	v_mfma_f32_16x16x32_bf16 v[76:79], v[100:103], v[228:231], v[76:79]
	s_setprio 0
	s_setprio 1
	v_mfma_f32_16x16x32_bf16 v[132:135], v[136:139], v[160:163], v[132:135]
	v_mfma_f32_16x16x32_bf16 v[132:135], v[148:151], v[164:167], v[132:135]
	v_mfma_f32_16x16x32_bf16 v[128:131], v[152:155], v[160:163], v[128:131]
	v_mfma_f32_16x16x32_bf16 v[128:131], v[156:159], v[164:167], v[128:131]
	v_mfma_f32_16x16x32_bf16 v[104:107], v[152:155], v[168:171], v[104:107]
	v_mfma_f32_16x16x32_bf16 v[104:107], v[156:159], v[172:175], v[104:107]
	v_mfma_f32_16x16x32_bf16 v[108:111], v[136:139], v[168:171], v[108:111]
	v_mfma_f32_16x16x32_bf16 v[108:111], v[148:151], v[172:175], v[108:111]
	v_mfma_f32_16x16x32_bf16 v[84:87], v[136:139], v[176:179], v[84:87]
	v_mfma_f32_16x16x32_bf16 v[84:87], v[148:151], v[180:183], v[84:87]
	v_mfma_f32_16x16x32_bf16 v[80:83], v[152:155], v[176:179], v[80:83]
	v_mfma_f32_16x16x32_bf16 v[80:83], v[156:159], v[180:183], v[80:83]
	v_mfma_f32_16x16x32_bf16 v[64:67], v[152:155], v[202:205], v[64:67]
	v_mfma_f32_16x16x32_bf16 v[64:67], v[156:159], v[228:231], v[64:67]
	v_mfma_f32_16x16x32_bf16 v[68:71], v[136:139], v[202:205], v[68:71]
	v_mfma_f32_16x16x32_bf16 v[68:71], v[148:151], v[228:231], v[68:71]
	s_setprio 0
	s_barrier
	s_add_i32 s46, s58, s2
	v_lshl_add_u64 v[208:209], v[208:209], 0, s[24:25]
	s_mov_b32 m0, s46
	ds_read_b128 v[160:163], v238 offset:49152
	ds_read_b128 v[164:167], v238 offset:50176
	ds_read_b128 v[168:171], v238 offset:51200
	ds_read_b128 v[172:175], v238 offset:52224
	ds_read_b128 v[176:179], v238 offset:53248
	ds_read_b128 v[180:183], v238 offset:54272
	ds_read_b128 v[202:205], v238 offset:55296
	ds_read_b128 v[228:231], v238 offset:56320
	global_load_lds_dwordx4 v[208:209], off
	s_add_i32 m0, s46, 0x2000
	s_add_u32 s44, s44, 0x40080
	v_lshl_add_u64 v[208:209], v[212:213], 0, s[24:25]
	s_addc_u32 s45, s45, 0
	s_add_i32 s46, s59, s2
	global_load_lds_dwordx4 v[208:209], off
	v_lshl_add_u64 v[208:209], s[44:45], 0, v[186:187]
	s_mov_b32 m0, s46
	s_nop 0
	global_load_lds_dwordx4 v[208:209], off
	v_lshl_add_u64 v[208:209], s[44:45], 0, v[190:191]
	s_add_i32 m0, s46, 0x2000
	s_nop 0
	global_load_lds_dwordx4 v[208:209], off
	v_lshl_add_u64 v[208:209], v[216:217], 0, s[24:25]
	s_mov_b32 m0, s49
	s_nop 0
	global_load_lds_dwordx4 v[208:209], off
	v_lshl_add_u64 v[208:209], v[220:221], 0, s[24:25]
	s_mov_b32 m0, s50
	s_nop 0
	global_load_lds_dwordx4 v[208:209], off
	s_waitcnt vmcnt(8)
	s_waitcnt lgkmcnt(0)
	s_barrier
	s_setprio 1
	s_waitcnt lgkmcnt(0)
	v_mfma_f32_16x16x32_bf16 v[60:63], v[88:91], v[160:163], v[60:63]
	v_mfma_f32_16x16x32_bf16 v[60:63], v[100:103], v[164:167], v[60:63]
	v_mfma_f32_16x16x32_bf16 v[56:59], v[112:115], v[160:163], v[56:59]
	v_mfma_f32_16x16x32_bf16 v[56:59], v[124:127], v[164:167], v[56:59]
	v_mfma_f32_16x16x32_bf16 v[40:43], v[112:115], v[168:171], v[40:43]
	v_mfma_f32_16x16x32_bf16 v[40:43], v[124:127], v[172:175], v[40:43]
	v_mfma_f32_16x16x32_bf16 v[44:47], v[88:91], v[168:171], v[44:47]
	v_mfma_f32_16x16x32_bf16 v[44:47], v[100:103], v[172:175], v[44:47]
	v_mfma_f32_16x16x32_bf16 v[28:31], v[88:91], v[176:179], v[28:31]
	v_mfma_f32_16x16x32_bf16 v[28:31], v[100:103], v[180:183], v[28:31]
	v_mfma_f32_16x16x32_bf16 v[24:27], v[112:115], v[176:179], v[24:27]
	v_mfma_f32_16x16x32_bf16 v[24:27], v[124:127], v[180:183], v[24:27]
	v_mfma_f32_16x16x32_bf16 v[8:11], v[112:115], v[202:205], v[8:11]
	v_mfma_f32_16x16x32_bf16 v[8:11], v[124:127], v[228:231], v[8:11]
	v_mfma_f32_16x16x32_bf16 v[12:15], v[88:91], v[202:205], v[12:15]
	v_mfma_f32_16x16x32_bf16 v[12:15], v[100:103], v[228:231], v[12:15]
	s_setprio 0
	s_setprio 1
	v_mfma_f32_16x16x32_bf16 v[52:55], v[136:139], v[160:163], v[52:55]
	v_mfma_f32_16x16x32_bf16 v[52:55], v[148:151], v[164:167], v[52:55]
	v_mfma_f32_16x16x32_bf16 v[48:51], v[152:155], v[160:163], v[48:51]
	v_mfma_f32_16x16x32_bf16 v[48:51], v[156:159], v[164:167], v[48:51]
	v_mfma_f32_16x16x32_bf16 v[32:35], v[152:155], v[168:171], v[32:35]
	v_mfma_f32_16x16x32_bf16 v[32:35], v[156:159], v[172:175], v[32:35]
	v_mfma_f32_16x16x32_bf16 v[36:39], v[136:139], v[168:171], v[36:39]
	v_mfma_f32_16x16x32_bf16 v[36:39], v[148:151], v[172:175], v[36:39]
	v_mfma_f32_16x16x32_bf16 v[20:23], v[136:139], v[176:179], v[20:23]
	v_mfma_f32_16x16x32_bf16 v[20:23], v[148:151], v[180:183], v[20:23]
	v_mfma_f32_16x16x32_bf16 v[16:19], v[152:155], v[176:179], v[16:19]
	v_mfma_f32_16x16x32_bf16 v[16:19], v[156:159], v[180:183], v[16:19]
	v_mfma_f32_16x16x32_bf16 v[0:3], v[152:155], v[202:205], v[0:3]
	v_mfma_f32_16x16x32_bf16 v[0:3], v[156:159], v[228:231], v[0:3]
	v_mfma_f32_16x16x32_bf16 v[4:7], v[136:139], v[202:205], v[4:7]
	v_mfma_f32_16x16x32_bf16 v[4:7], v[148:151], v[228:231], v[4:7]
	s_setprio 0
	s_barrier
	s_add_i32 s57, s57, 2
	s_add_u32 s42, s42, 0x100
	s_addc_u32 s43, s43, 0
	s_add_u32 s55, s55, 0x100
	s_addc_u32 s56, s56, 0
	s_cmp_gt_u32 s57, 13
	s_cbranch_scc0 .LBB0_646
	s_and_b64 vcc, exec, s[26:27]
	s_cbranch_vccz .LBB0_649
	s_barrier

.LBB0_751:
	ds_read_b128 v[156:159], v152
	ds_read_b128 v[160:163], v152 offset:1024
	ds_read_b128 v[164:167], v152 offset:2048
	ds_read_b128 v[168:171], v152 offset:3072
	ds_read_b128 v[172:175], v153
	ds_read_b128 v[176:179], v153 offset:1024
	ds_read_b128 v[180:183], v153 offset:2048
	ds_read_b128 v[184:187], v153 offset:3072
	s_add_u32 s38, s36, 0xfffc0080
	s_addc_u32 s39, s37, -1
	s_cmp_eq_u32 s54, 12
	s_cselect_b32 s41, s25, s39
	s_cselect_b32 s40, s50, s38
	s_cselect_b32 s39, s23, s53
	s_cselect_b32 s38, s51, s52
	v_lshl_add_u64 v[146:147], s[36:37], 0, v[138:139]
	s_add_i32 m0, s31, 0xc000
	ds_read_b128 v[188:191], v154
	ds_read_b128 v[192:195], v154 offset:1024
	ds_read_b128 v[196:199], v154 offset:2048
	ds_read_b128 v[200:203], v154 offset:3072
	ds_read_b128 v[204:207], v154 offset:4096
	ds_read_b128 v[208:211], v154 offset:5120
	ds_read_b128 v[216:219], v154 offset:6144
	ds_read_b128 v[220:223], v154 offset:7168
	global_load_lds_dwordx4 v[146:147], off
	v_lshl_add_u64 v[146:147], s[36:37], 0, v[140:141]
	s_add_i32 m0, s31, 0xe000
	s_nop 0
	global_load_lds_dwordx4 v[146:147], off
	s_waitcnt vmcnt(8)
	s_waitcnt lgkmcnt(0)
	s_barrier
	s_setprio 1
	s_waitcnt lgkmcnt(0)
	v_mfma_f32_16x16x32_bf16 v[124:127], v[156:159], v[188:191], v[124:127]
	v_mfma_f32_16x16x32_bf16 v[124:127], v[160:163], v[192:195], v[124:127]
	v_mfma_f32_16x16x32_bf16 v[120:123], v[164:167], v[188:191], v[120:123]
	v_mfma_f32_16x16x32_bf16 v[120:123], v[168:171], v[192:195], v[120:123]
	v_mfma_f32_16x16x32_bf16 v[104:107], v[164:167], v[196:199], v[104:107]
	v_mfma_f32_16x16x32_bf16 v[104:107], v[168:171], v[200:203], v[104:107]
	v_mfma_f32_16x16x32_bf16 v[108:111], v[156:159], v[196:199], v[108:111]
	v_mfma_f32_16x16x32_bf16 v[108:111], v[160:163], v[200:203], v[108:111]
	v_mfma_f32_16x16x32_bf16 v[92:95], v[156:159], v[204:207], v[92:95]
	v_mfma_f32_16x16x32_bf16 v[92:95], v[160:163], v[208:211], v[92:95]
	v_mfma_f32_16x16x32_bf16 v[88:91], v[164:167], v[204:207], v[88:91]
	v_mfma_f32_16x16x32_bf16 v[88:91], v[168:171], v[208:211], v[88:91]
	v_mfma_f32_16x16x32_bf16 v[72:75], v[164:167], v[216:219], v[72:75]
	v_mfma_f32_16x16x32_bf16 v[72:75], v[168:171], v[220:223], v[72:75]
	v_mfma_f32_16x16x32_bf16 v[76:79], v[156:159], v[216:219], v[76:79]
	v_mfma_f32_16x16x32_bf16 v[76:79], v[160:163], v[220:223], v[76:79]
	s_setprio 0
	s_setprio 1
	v_mfma_f32_16x16x32_bf16 v[116:119], v[172:175], v[188:191], v[116:119]
	v_mfma_f32_16x16x32_bf16 v[116:119], v[176:179], v[192:195], v[116:119]
	v_mfma_f32_16x16x32_bf16 v[112:115], v[180:183], v[188:191], v[112:115]
	v_mfma_f32_16x16x32_bf16 v[112:115], v[184:187], v[192:195], v[112:115]
	v_mfma_f32_16x16x32_bf16 v[96:99], v[180:183], v[196:199], v[96:99]
	v_mfma_f32_16x16x32_bf16 v[96:99], v[184:187], v[200:203], v[96:99]
	v_mfma_f32_16x16x32_bf16 v[100:103], v[172:175], v[196:199], v[100:103]
	v_mfma_f32_16x16x32_bf16 v[100:103], v[176:179], v[200:203], v[100:103]
	v_mfma_f32_16x16x32_bf16 v[84:87], v[172:175], v[204:207], v[84:87]
	v_mfma_f32_16x16x32_bf16 v[84:87], v[176:179], v[208:211], v[84:87]
	v_mfma_f32_16x16x32_bf16 v[80:83], v[180:183], v[204:207], v[80:83]
	v_mfma_f32_16x16x32_bf16 v[80:83], v[184:187], v[208:211], v[80:83]
	v_mfma_f32_16x16x32_bf16 v[64:67], v[180:183], v[216:219], v[64:67]
	v_mfma_f32_16x16x32_bf16 v[64:67], v[184:187], v[220:223], v[64:67]
	v_mfma_f32_16x16x32_bf16 v[68:71], v[172:175], v[216:219], v[68:71]
	v_mfma_f32_16x16x32_bf16 v[68:71], v[176:179], v[220:223], v[68:71]
	s_setprio 0
	s_barrier
	s_add_i32 s55, s47, s33
	v_lshl_add_u64 v[146:147], s[38:39], 0, v[132:133]
	s_mov_b32 m0, s55
	ds_read_b128 v[188:191], v154 offset:16384
	ds_read_b128 v[192:195], v154 offset:17408
	ds_read_b128 v[196:199], v154 offset:18432
	ds_read_b128 v[200:203], v154 offset:19456
	ds_read_b128 v[204:207], v154 offset:20480
	ds_read_b128 v[208:211], v154 offset:21504
	ds_read_b128 v[216:219], v154 offset:22528
	ds_read_b128 v[220:223], v154 offset:23552
	global_load_lds_dwordx4 v[146:147], off
	s_add_i32 m0, s55, 0x2000
	s_add_u32 s56, s38, 0x40000
	v_lshl_add_u64 v[212:213], s[38:39], 0, v[128:129]
	s_addc_u32 s57, s39, 0
	s_add_i32 s55, s48, s33
	global_load_lds_dwordx4 v[212:213], off
	v_lshl_add_u64 v[224:225], s[56:57], 0, v[132:133]
	s_mov_b32 m0, s55
	v_lshl_add_u64 v[226:227], s[40:41], 0, v[130:131]
	global_load_lds_dwordx4 v[224:225], off
	v_lshl_add_u64 v[224:225], s[56:57], 0, v[128:129]
	s_add_i32 m0, s55, 0x2000
	s_nop 0
	global_load_lds_dwordx4 v[224:225], off
	v_lshl_add_u64 v[224:225], s[40:41], 0, v[134:135]
	s_mov_b32 m0, s31
	s_nop 0
	global_load_lds_dwordx4 v[224:225], off
	s_mov_b32 m0, s34
	s_nop 0
	global_load_lds_dwordx4 v[226:227], off
	s_waitcnt vmcnt(8)
	s_waitcnt lgkmcnt(0)
	s_barrier
	s_setprio 1
	s_waitcnt lgkmcnt(0)
	v_mfma_f32_16x16x32_bf16 v[60:63], v[156:159], v[188:191], v[60:63]
	v_mfma_f32_16x16x32_bf16 v[60:63], v[160:163], v[192:195], v[60:63]
	v_mfma_f32_16x16x32_bf16 v[56:59], v[164:167], v[188:191], v[56:59]
	v_mfma_f32_16x16x32_bf16 v[56:59], v[168:171], v[192:195], v[56:59]
	v_mfma_f32_16x16x32_bf16 v[40:43], v[164:167], v[196:199], v[40:43]
	v_mfma_f32_16x16x32_bf16 v[40:43], v[168:171], v[200:203], v[40:43]
	v_mfma_f32_16x16x32_bf16 v[44:47], v[156:159], v[196:199], v[44:47]
	v_mfma_f32_16x16x32_bf16 v[44:47], v[160:163], v[200:203], v[44:47]
	v_mfma_f32_16x16x32_bf16 v[28:31], v[156:159], v[204:207], v[28:31]
	v_mfma_f32_16x16x32_bf16 v[28:31], v[160:163], v[208:211], v[28:31]
	v_mfma_f32_16x16x32_bf16 v[24:27], v[164:167], v[204:207], v[24:27]
	v_mfma_f32_16x16x32_bf16 v[24:27], v[168:171], v[208:211], v[24:27]
	v_mfma_f32_16x16x32_bf16 v[8:11], v[164:167], v[216:219], v[8:11]
	v_mfma_f32_16x16x32_bf16 v[8:11], v[168:171], v[220:223], v[8:11]
	v_mfma_f32_16x16x32_bf16 v[12:15], v[156:159], v[216:219], v[12:15]
	v_mfma_f32_16x16x32_bf16 v[12:15], v[160:163], v[220:223], v[12:15]
	s_setprio 0
	s_setprio 1
	v_mfma_f32_16x16x32_bf16 v[52:55], v[172:175], v[188:191], v[52:55]
	v_mfma_f32_16x16x32_bf16 v[52:55], v[176:179], v[192:195], v[52:55]
	v_mfma_f32_16x16x32_bf16 v[48:51], v[180:183], v[188:191], v[48:51]
	v_mfma_f32_16x16x32_bf16 v[48:51], v[184:187], v[192:195], v[48:51]
	v_mfma_f32_16x16x32_bf16 v[32:35], v[180:183], v[196:199], v[32:35]
	v_mfma_f32_16x16x32_bf16 v[32:35], v[184:187], v[200:203], v[32:35]
	v_mfma_f32_16x16x32_bf16 v[36:39], v[172:175], v[196:199], v[36:39]
	v_mfma_f32_16x16x32_bf16 v[36:39], v[176:179], v[200:203], v[36:39]
	v_mfma_f32_16x16x32_bf16 v[20:23], v[172:175], v[204:207], v[20:23]
	v_mfma_f32_16x16x32_bf16 v[20:23], v[176:179], v[208:211], v[20:23]
	v_mfma_f32_16x16x32_bf16 v[16:19], v[180:183], v[204:207], v[16:19]
	v_mfma_f32_16x16x32_bf16 v[16:19], v[184:187], v[208:211], v[16:19]
	v_mfma_f32_16x16x32_bf16 v[0:3], v[180:183], v[216:219], v[0:3]
	v_mfma_f32_16x16x32_bf16 v[0:3], v[184:187], v[220:223], v[0:3]
	v_mfma_f32_16x16x32_bf16 v[4:7], v[172:175], v[216:219], v[4:7]
	v_mfma_f32_16x16x32_bf16 v[4:7], v[176:179], v[220:223], v[4:7]
	s_setprio 0
	s_barrier
	s_add_i32 s55, 0, 0x18000
	v_add_u32_e32 v155, s55, v148
	s_add_i32 s56, 0, 0x1c000
	ds_read_b128 v[156:159], v155
	ds_read_b128 v[160:163], v155 offset:1024
	ds_read_b128 v[164:167], v155 offset:2048
	ds_read_b128 v[168:171], v155 offset:3072
	v_add_u32_e32 v155, s56, v148
	ds_read_b128 v[172:175], v155
	ds_read_b128 v[176:179], v155 offset:1024
	ds_read_b128 v[180:183], v155 offset:2048
	ds_read_b128 v[184:187], v155 offset:3072
	s_add_u32 s40, s40, 0x40000
	s_addc_u32 s41, s41, 0
	s_mov_b32 m0, s35
	v_lshl_add_u64 v[228:229], s[40:41], 0, v[134:135]
	ds_read_b128 v[188:191], v154 offset:32768
	ds_read_b128 v[192:195], v154 offset:33792
	ds_read_b128 v[196:199], v154 offset:34816
	ds_read_b128 v[200:203], v154 offset:35840
	ds_read_b128 v[204:207], v154 offset:36864
	ds_read_b128 v[208:211], v154 offset:37888
	ds_read_b128 v[216:219], v154 offset:38912
	ds_read_b128 v[220:223], v154 offset:39936
	global_load_lds_dwordx4 v[228:229], off
	v_lshl_add_u64 v[228:229], s[40:41], 0, v[130:131]
	s_mov_b32 m0, s42
	s_nop 0
	global_load_lds_dwordx4 v[228:229], off
	s_waitcnt vmcnt(8)
	s_waitcnt lgkmcnt(0)
	s_barrier
	s_setprio 1
	s_waitcnt lgkmcnt(0)
	v_mfma_f32_16x16x32_bf16 v[124:127], v[156:159], v[188:191], v[124:127]
	v_mfma_f32_16x16x32_bf16 v[124:127], v[160:163], v[192:195], v[124:127]
	v_mfma_f32_16x16x32_bf16 v[120:123], v[164:167], v[188:191], v[120:123]
	v_mfma_f32_16x16x32_bf16 v[120:123], v[168:171], v[192:195], v[120:123]
	v_mfma_f32_16x16x32_bf16 v[104:107], v[164:167], v[196:199], v[104:107]
	v_mfma_f32_16x16x32_bf16 v[104:107], v[168:171], v[200:203], v[104:107]
	v_mfma_f32_16x16x32_bf16 v[108:111], v[156:159], v[196:199], v[108:111]
	v_mfma_f32_16x16x32_bf16 v[108:111], v[160:163], v[200:203], v[108:111]
	v_mfma_f32_16x16x32_bf16 v[92:95], v[156:159], v[204:207], v[92:95]
	v_mfma_f32_16x16x32_bf16 v[92:95], v[160:163], v[208:211], v[92:95]
	v_mfma_f32_16x16x32_bf16 v[88:91], v[164:167], v[204:207], v[88:91]
	v_mfma_f32_16x16x32_bf16 v[88:91], v[168:171], v[208:211], v[88:91]
	v_mfma_f32_16x16x32_bf16 v[72:75], v[164:167], v[216:219], v[72:75]
	v_mfma_f32_16x16x32_bf16 v[72:75], v[168:171], v[220:223], v[72:75]
	v_mfma_f32_16x16x32_bf16 v[76:79], v[156:159], v[216:219], v[76:79]
	v_mfma_f32_16x16x32_bf16 v[76:79], v[160:163], v[220:223], v[76:79]
	s_setprio 0
	s_setprio 1
	v_mfma_f32_16x16x32_bf16 v[116:119], v[172:175], v[188:191], v[116:119]
	v_mfma_f32_16x16x32_bf16 v[116:119], v[176:179], v[192:195], v[116:119]
	v_mfma_f32_16x16x32_bf16 v[112:115], v[180:183], v[188:191], v[112:115]
	v_mfma_f32_16x16x32_bf16 v[112:115], v[184:187], v[192:195], v[112:115]
	v_mfma_f32_16x16x32_bf16 v[96:99], v[180:183], v[196:199], v[96:99]
	v_mfma_f32_16x16x32_bf16 v[96:99], v[184:187], v[200:203], v[96:99]
	v_mfma_f32_16x16x32_bf16 v[100:103], v[172:175], v[196:199], v[100:103]
	v_mfma_f32_16x16x32_bf16 v[100:103], v[176:179], v[200:203], v[100:103]
	v_mfma_f32_16x16x32_bf16 v[84:87], v[172:175], v[204:207], v[84:87]
	v_mfma_f32_16x16x32_bf16 v[84:87], v[176:179], v[208:211], v[84:87]
	v_mfma_f32_16x16x32_bf16 v[80:83], v[180:183], v[204:207], v[80:83]
	v_mfma_f32_16x16x32_bf16 v[80:83], v[184:187], v[208:211], v[80:83]
	v_mfma_f32_16x16x32_bf16 v[64:67], v[180:183], v[216:219], v[64:67]
	v_mfma_f32_16x16x32_bf16 v[64:67], v[184:187], v[220:223], v[64:67]
	v_mfma_f32_16x16x32_bf16 v[68:71], v[172:175], v[216:219], v[68:71]
	v_mfma_f32_16x16x32_bf16 v[68:71], v[176:179], v[220:223], v[68:71]
	s_setprio 0
	s_barrier
	s_add_i32 s40, s55, s33
	v_lshl_add_u64 v[146:147], v[146:147], 0, s[18:19]
	s_mov_b32 m0, s40
	ds_read_b128 v[188:191], v154 offset:49152
	ds_read_b128 v[192:195], v154 offset:50176
	ds_read_b128 v[196:199], v154 offset:51200
	ds_read_b128 v[200:203], v154 offset:52224
	ds_read_b128 v[204:207], v154 offset:53248
	ds_read_b128 v[208:211], v154 offset:54272
	ds_read_b128 v[216:219], v154 offset:55296
	ds_read_b128 v[220:223], v154 offset:56320
	global_load_lds_dwordx4 v[146:147], off
	s_add_i32 m0, s40, 0x2000
	s_add_u32 s38, s38, 0x40080
	v_lshl_add_u64 v[146:147], v[212:213], 0, s[18:19]
	s_addc_u32 s39, s39, 0
	s_add_i32 s40, s56, s33
	global_load_lds_dwordx4 v[146:147], off
	v_lshl_add_u64 v[146:147], s[38:39], 0, v[132:133]
	s_mov_b32 m0, s40
	s_nop 0
	global_load_lds_dwordx4 v[146:147], off
	v_lshl_add_u64 v[146:147], s[38:39], 0, v[128:129]
	s_add_i32 m0, s40, 0x2000
	s_nop 0
	global_load_lds_dwordx4 v[146:147], off
	v_lshl_add_u64 v[146:147], v[224:225], 0, s[18:19]
	s_mov_b32 m0, s44
	s_nop 0
	global_load_lds_dwordx4 v[146:147], off
	v_lshl_add_u64 v[146:147], v[226:227], 0, s[18:19]
	s_mov_b32 m0, s45
	s_nop 0
	global_load_lds_dwordx4 v[146:147], off
	s_waitcnt vmcnt(8)
	s_waitcnt lgkmcnt(0)
	s_barrier
	s_setprio 1
	s_waitcnt lgkmcnt(0)
	v_mfma_f32_16x16x32_bf16 v[60:63], v[156:159], v[188:191], v[60:63]
	v_mfma_f32_16x16x32_bf16 v[60:63], v[160:163], v[192:195], v[60:63]
	v_mfma_f32_16x16x32_bf16 v[56:59], v[164:167], v[188:191], v[56:59]
	v_mfma_f32_16x16x32_bf16 v[56:59], v[168:171], v[192:195], v[56:59]
	v_mfma_f32_16x16x32_bf16 v[40:43], v[164:167], v[196:199], v[40:43]
	v_mfma_f32_16x16x32_bf16 v[40:43], v[168:171], v[200:203], v[40:43]
	v_mfma_f32_16x16x32_bf16 v[44:47], v[156:159], v[196:199], v[44:47]
	v_mfma_f32_16x16x32_bf16 v[44:47], v[160:163], v[200:203], v[44:47]
	v_mfma_f32_16x16x32_bf16 v[28:31], v[156:159], v[204:207], v[28:31]
	v_mfma_f32_16x16x32_bf16 v[28:31], v[160:163], v[208:211], v[28:31]
	v_mfma_f32_16x16x32_bf16 v[24:27], v[164:167], v[204:207], v[24:27]
	v_mfma_f32_16x16x32_bf16 v[24:27], v[168:171], v[208:211], v[24:27]
	v_mfma_f32_16x16x32_bf16 v[8:11], v[164:167], v[216:219], v[8:11]
	v_mfma_f32_16x16x32_bf16 v[8:11], v[168:171], v[220:223], v[8:11]
	v_mfma_f32_16x16x32_bf16 v[12:15], v[156:159], v[216:219], v[12:15]
	v_mfma_f32_16x16x32_bf16 v[12:15], v[160:163], v[220:223], v[12:15]
	s_setprio 0
	s_setprio 1
	v_mfma_f32_16x16x32_bf16 v[52:55], v[172:175], v[188:191], v[52:55]
	v_mfma_f32_16x16x32_bf16 v[52:55], v[176:179], v[192:195], v[52:55]
	v_mfma_f32_16x16x32_bf16 v[48:51], v[180:183], v[188:191], v[48:51]
	v_mfma_f32_16x16x32_bf16 v[48:51], v[184:187], v[192:195], v[48:51]
	v_mfma_f32_16x16x32_bf16 v[32:35], v[180:183], v[196:199], v[32:35]
	v_mfma_f32_16x16x32_bf16 v[32:35], v[184:187], v[200:203], v[32:35]
	v_mfma_f32_16x16x32_bf16 v[36:39], v[172:175], v[196:199], v[36:39]
	v_mfma_f32_16x16x32_bf16 v[36:39], v[176:179], v[200:203], v[36:39]
	v_mfma_f32_16x16x32_bf16 v[20:23], v[172:175], v[204:207], v[20:23]
	v_mfma_f32_16x16x32_bf16 v[20:23], v[176:179], v[208:211], v[20:23]
	v_mfma_f32_16x16x32_bf16 v[16:19], v[180:183], v[204:207], v[16:19]
	v_mfma_f32_16x16x32_bf16 v[16:19], v[184:187], v[208:211], v[16:19]
	v_mfma_f32_16x16x32_bf16 v[0:3], v[180:183], v[216:219], v[0:3]
	v_mfma_f32_16x16x32_bf16 v[0:3], v[184:187], v[220:223], v[0:3]
	v_mfma_f32_16x16x32_bf16 v[4:7], v[172:175], v[216:219], v[4:7]
	v_mfma_f32_16x16x32_bf16 v[4:7], v[176:179], v[220:223], v[4:7]
	s_setprio 0
	s_barrier
	s_add_i32 s54, s54, 2
	s_add_u32 s36, s36, 0x100
	s_addc_u32 s37, s37, 0
	s_add_u32 s52, s52, 0x100
	s_addc_u32 s53, s53, 0
	s_cmp_gt_u32 s54, 13
	s_cbranch_scc0 .LBB0_751
	s_and_b64 vcc, exec, s[20:21]
	s_cbranch_vccz .LBB0_754
	s_barrier

.LBB0_828:
	ds_read_b128 v[142:145], v195
	ds_read_b128 v[146:149], v195 offset:1024
	ds_read_b128 v[150:153], v195 offset:2048
	ds_read_b128 v[154:157], v195 offset:3072
	ds_read_b128 v[158:161], v196
	ds_read_b128 v[162:165], v196 offset:1024
	ds_read_b128 v[166:169], v196 offset:2048
	ds_read_b128 v[170:173], v196 offset:3072
	s_add_u32 s40, s38, 0xfff00080
	s_addc_u32 s41, s39, -1
	s_cmp_eq_u32 s58, 60
	s_cselect_b32 s43, s27, s41
	s_cselect_b32 s42, s54, s40
	s_cselect_b32 s41, s25, s57
	s_cselect_b32 s40, s55, s56
	v_lshl_add_u64 v[190:191], s[38:39], 0, v[134:135]
	s_add_i32 m0, s2, 0xc000
	ds_read_b128 v[174:177], v197
	ds_read_b128 v[178:181], v197 offset:1024
	ds_read_b128 v[182:185], v197 offset:2048
	ds_read_b128 v[186:189], v197 offset:3072
	ds_read_b128 v[198:201], v197 offset:4096
	ds_read_b128 v[202:205], v197 offset:5120
	ds_read_b128 v[206:209], v197 offset:6144
	ds_read_b128 v[210:213], v197 offset:7168
	global_load_lds_dwordx4 v[190:191], off
	v_lshl_add_u64 v[190:191], s[38:39], 0, v[136:137]
	s_add_i32 m0, s2, 0xe000
	s_nop 0
	global_load_lds_dwordx4 v[190:191], off
	s_waitcnt vmcnt(8)
	s_waitcnt lgkmcnt(0)
	s_barrier
	s_setprio 1
	s_waitcnt lgkmcnt(0)
	v_mfma_f32_16x16x32_bf16 v[124:127], v[142:145], v[174:177], v[124:127]
	v_mfma_f32_16x16x32_bf16 v[124:127], v[146:149], v[178:181], v[124:127]
	v_mfma_f32_16x16x32_bf16 v[120:123], v[150:153], v[174:177], v[120:123]
	v_mfma_f32_16x16x32_bf16 v[120:123], v[154:157], v[178:181], v[120:123]
	v_mfma_f32_16x16x32_bf16 v[104:107], v[150:153], v[182:185], v[104:107]
	v_mfma_f32_16x16x32_bf16 v[104:107], v[154:157], v[186:189], v[104:107]
	v_mfma_f32_16x16x32_bf16 v[108:111], v[142:145], v[182:185], v[108:111]
	v_mfma_f32_16x16x32_bf16 v[108:111], v[146:149], v[186:189], v[108:111]
	v_mfma_f32_16x16x32_bf16 v[92:95], v[142:145], v[198:201], v[92:95]
	v_mfma_f32_16x16x32_bf16 v[92:95], v[146:149], v[202:205], v[92:95]
	v_mfma_f32_16x16x32_bf16 v[88:91], v[150:153], v[198:201], v[88:91]
	v_mfma_f32_16x16x32_bf16 v[88:91], v[154:157], v[202:205], v[88:91]
	v_mfma_f32_16x16x32_bf16 v[72:75], v[150:153], v[206:209], v[72:75]
	v_mfma_f32_16x16x32_bf16 v[72:75], v[154:157], v[210:213], v[72:75]
	v_mfma_f32_16x16x32_bf16 v[76:79], v[142:145], v[206:209], v[76:79]
	v_mfma_f32_16x16x32_bf16 v[76:79], v[146:149], v[210:213], v[76:79]
	s_setprio 0
	s_setprio 1
	v_mfma_f32_16x16x32_bf16 v[116:119], v[158:161], v[174:177], v[116:119]
	v_mfma_f32_16x16x32_bf16 v[116:119], v[162:165], v[178:181], v[116:119]
	v_mfma_f32_16x16x32_bf16 v[112:115], v[166:169], v[174:177], v[112:115]
	v_mfma_f32_16x16x32_bf16 v[112:115], v[170:173], v[178:181], v[112:115]
	v_mfma_f32_16x16x32_bf16 v[96:99], v[166:169], v[182:185], v[96:99]
	v_mfma_f32_16x16x32_bf16 v[96:99], v[170:173], v[186:189], v[96:99]
	v_mfma_f32_16x16x32_bf16 v[100:103], v[158:161], v[182:185], v[100:103]
	v_mfma_f32_16x16x32_bf16 v[100:103], v[162:165], v[186:189], v[100:103]
	v_mfma_f32_16x16x32_bf16 v[84:87], v[158:161], v[198:201], v[84:87]
	v_mfma_f32_16x16x32_bf16 v[84:87], v[162:165], v[202:205], v[84:87]
	v_mfma_f32_16x16x32_bf16 v[80:83], v[166:169], v[198:201], v[80:83]
	v_mfma_f32_16x16x32_bf16 v[80:83], v[170:173], v[202:205], v[80:83]
	v_mfma_f32_16x16x32_bf16 v[64:67], v[166:169], v[206:209], v[64:67]
	v_mfma_f32_16x16x32_bf16 v[64:67], v[170:173], v[210:213], v[64:67]
	v_mfma_f32_16x16x32_bf16 v[68:71], v[158:161], v[206:209], v[68:71]
	v_mfma_f32_16x16x32_bf16 v[68:71], v[162:165], v[210:213], v[68:71]
	s_setprio 0
	s_barrier
	s_add_i32 s59, s46, s3
	v_lshl_add_u64 v[190:191], s[40:41], 0, v[128:129]
	s_mov_b32 m0, s59
	ds_read_b128 v[174:177], v197 offset:16384
	ds_read_b128 v[178:181], v197 offset:17408
	ds_read_b128 v[182:185], v197 offset:18432
	ds_read_b128 v[186:189], v197 offset:19456
	ds_read_b128 v[198:201], v197 offset:20480
	ds_read_b128 v[202:205], v197 offset:21504
	ds_read_b128 v[206:209], v197 offset:22528
	ds_read_b128 v[210:213], v197 offset:23552
	global_load_lds_dwordx4 v[190:191], off
	s_add_i32 m0, s59, 0x2000
	s_add_u32 s62, s40, 0x100000
	v_lshl_add_u64 v[214:215], s[40:41], 0, v[130:131]
	s_addc_u32 s63, s41, 0
	s_add_i32 s59, s47, s3
	global_load_lds_dwordx4 v[214:215], off
	v_lshl_add_u64 v[216:217], s[62:63], 0, v[128:129]
	s_mov_b32 m0, s59
	v_lshl_add_u64 v[218:219], s[42:43], 0, v[130:131]
	global_load_lds_dwordx4 v[216:217], off
	v_lshl_add_u64 v[216:217], s[62:63], 0, v[130:131]
	s_add_i32 m0, s59, 0x2000
	s_nop 0
	global_load_lds_dwordx4 v[216:217], off
	v_lshl_add_u64 v[216:217], s[42:43], 0, v[128:129]
	s_mov_b32 m0, s2
	s_nop 0
	global_load_lds_dwordx4 v[216:217], off
	s_mov_b32 m0, s33
	s_nop 0
	global_load_lds_dwordx4 v[218:219], off
	s_waitcnt vmcnt(8)
	s_waitcnt lgkmcnt(0)
	s_barrier
	s_setprio 1
	s_waitcnt lgkmcnt(0)
	v_mfma_f32_16x16x32_bf16 v[60:63], v[142:145], v[174:177], v[60:63]
	v_mfma_f32_16x16x32_bf16 v[60:63], v[146:149], v[178:181], v[60:63]
	v_mfma_f32_16x16x32_bf16 v[56:59], v[150:153], v[174:177], v[56:59]
	v_mfma_f32_16x16x32_bf16 v[56:59], v[154:157], v[178:181], v[56:59]
	v_mfma_f32_16x16x32_bf16 v[40:43], v[150:153], v[182:185], v[40:43]
	v_mfma_f32_16x16x32_bf16 v[40:43], v[154:157], v[186:189], v[40:43]
	v_mfma_f32_16x16x32_bf16 v[44:47], v[142:145], v[182:185], v[44:47]
	v_mfma_f32_16x16x32_bf16 v[44:47], v[146:149], v[186:189], v[44:47]
	v_mfma_f32_16x16x32_bf16 v[28:31], v[142:145], v[198:201], v[28:31]
	v_mfma_f32_16x16x32_bf16 v[28:31], v[146:149], v[202:205], v[28:31]
	v_mfma_f32_16x16x32_bf16 v[24:27], v[150:153], v[198:201], v[24:27]
	v_mfma_f32_16x16x32_bf16 v[24:27], v[154:157], v[202:205], v[24:27]
	v_mfma_f32_16x16x32_bf16 v[8:11], v[150:153], v[206:209], v[8:11]
	v_mfma_f32_16x16x32_bf16 v[8:11], v[154:157], v[210:213], v[8:11]
	v_mfma_f32_16x16x32_bf16 v[12:15], v[142:145], v[206:209], v[12:15]
	v_mfma_f32_16x16x32_bf16 v[12:15], v[146:149], v[210:213], v[12:15]
	s_setprio 0
	s_setprio 1
	v_mfma_f32_16x16x32_bf16 v[52:55], v[158:161], v[174:177], v[52:55]
	v_mfma_f32_16x16x32_bf16 v[52:55], v[162:165], v[178:181], v[52:55]
	v_mfma_f32_16x16x32_bf16 v[48:51], v[166:169], v[174:177], v[48:51]
	v_mfma_f32_16x16x32_bf16 v[48:51], v[170:173], v[178:181], v[48:51]
	v_mfma_f32_16x16x32_bf16 v[32:35], v[166:169], v[182:185], v[32:35]
	v_mfma_f32_16x16x32_bf16 v[32:35], v[170:173], v[186:189], v[32:35]
	v_mfma_f32_16x16x32_bf16 v[36:39], v[158:161], v[182:185], v[36:39]
	v_mfma_f32_16x16x32_bf16 v[36:39], v[162:165], v[186:189], v[36:39]
	v_mfma_f32_16x16x32_bf16 v[20:23], v[158:161], v[198:201], v[20:23]
	v_mfma_f32_16x16x32_bf16 v[20:23], v[162:165], v[202:205], v[20:23]
	v_mfma_f32_16x16x32_bf16 v[16:19], v[166:169], v[198:201], v[16:19]
	v_mfma_f32_16x16x32_bf16 v[16:19], v[170:173], v[202:205], v[16:19]
	v_mfma_f32_16x16x32_bf16 v[0:3], v[166:169], v[206:209], v[0:3]
	v_mfma_f32_16x16x32_bf16 v[0:3], v[170:173], v[210:213], v[0:3]
	v_mfma_f32_16x16x32_bf16 v[4:7], v[158:161], v[206:209], v[4:7]
	v_mfma_f32_16x16x32_bf16 v[4:7], v[162:165], v[210:213], v[4:7]
	s_setprio 0
	s_barrier
	s_add_i32 s59, 0, 0x18000
	s_add_i32 s62, 0, 0x1c000
	v_add_u32_e32 v154, s59, v192
	v_add_u32_e32 v170, s62, v192
	ds_read_b128 v[142:145], v154
	ds_read_b128 v[146:149], v154 offset:1024
	ds_read_b128 v[150:153], v154 offset:2048
	ds_read_b128 v[154:157], v154 offset:3072
	ds_read_b128 v[158:161], v170
	ds_read_b128 v[162:165], v170 offset:1024
	ds_read_b128 v[166:169], v170 offset:2048
	ds_read_b128 v[170:173], v170 offset:3072
	s_add_u32 s42, s42, 0x100000
	s_addc_u32 s43, s43, 0
	s_mov_b32 m0, s34
	v_lshl_add_u64 v[220:221], s[42:43], 0, v[128:129]
	ds_read_b128 v[174:177], v197 offset:32768
	ds_read_b128 v[178:181], v197 offset:33792
	ds_read_b128 v[182:185], v197 offset:34816
	ds_read_b128 v[186:189], v197 offset:35840
	ds_read_b128 v[198:201], v197 offset:36864
	ds_read_b128 v[202:205], v197 offset:37888
	ds_read_b128 v[206:209], v197 offset:38912
	ds_read_b128 v[210:213], v197 offset:39936
	global_load_lds_dwordx4 v[220:221], off
	v_lshl_add_u64 v[220:221], s[42:43], 0, v[130:131]
	s_mov_b32 m0, s35
	s_nop 0
	global_load_lds_dwordx4 v[220:221], off
	s_waitcnt vmcnt(8)
	s_waitcnt lgkmcnt(0)
	s_barrier
	s_setprio 1
	s_waitcnt lgkmcnt(0)
	v_mfma_f32_16x16x32_bf16 v[124:127], v[142:145], v[174:177], v[124:127]
	v_mfma_f32_16x16x32_bf16 v[124:127], v[146:149], v[178:181], v[124:127]
	v_mfma_f32_16x16x32_bf16 v[120:123], v[150:153], v[174:177], v[120:123]
	v_mfma_f32_16x16x32_bf16 v[120:123], v[154:157], v[178:181], v[120:123]
	v_mfma_f32_16x16x32_bf16 v[104:107], v[150:153], v[182:185], v[104:107]
	v_mfma_f32_16x16x32_bf16 v[104:107], v[154:157], v[186:189], v[104:107]
	v_mfma_f32_16x16x32_bf16 v[108:111], v[142:145], v[182:185], v[108:111]
	v_mfma_f32_16x16x32_bf16 v[108:111], v[146:149], v[186:189], v[108:111]
	v_mfma_f32_16x16x32_bf16 v[92:95], v[142:145], v[198:201], v[92:95]
	v_mfma_f32_16x16x32_bf16 v[92:95], v[146:149], v[202:205], v[92:95]
	v_mfma_f32_16x16x32_bf16 v[88:91], v[150:153], v[198:201], v[88:91]
	v_mfma_f32_16x16x32_bf16 v[88:91], v[154:157], v[202:205], v[88:91]
	v_mfma_f32_16x16x32_bf16 v[72:75], v[150:153], v[206:209], v[72:75]
	v_mfma_f32_16x16x32_bf16 v[72:75], v[154:157], v[210:213], v[72:75]
	v_mfma_f32_16x16x32_bf16 v[76:79], v[142:145], v[206:209], v[76:79]
	v_mfma_f32_16x16x32_bf16 v[76:79], v[146:149], v[210:213], v[76:79]
	s_setprio 0
	s_setprio 1
	v_mfma_f32_16x16x32_bf16 v[116:119], v[158:161], v[174:177], v[116:119]
	v_mfma_f32_16x16x32_bf16 v[116:119], v[162:165], v[178:181], v[116:119]
	v_mfma_f32_16x16x32_bf16 v[112:115], v[166:169], v[174:177], v[112:115]
	v_mfma_f32_16x16x32_bf16 v[112:115], v[170:173], v[178:181], v[112:115]
	v_mfma_f32_16x16x32_bf16 v[96:99], v[166:169], v[182:185], v[96:99]
	v_mfma_f32_16x16x32_bf16 v[96:99], v[170:173], v[186:189], v[96:99]
	v_mfma_f32_16x16x32_bf16 v[100:103], v[158:161], v[182:185], v[100:103]
	v_mfma_f32_16x16x32_bf16 v[100:103], v[162:165], v[186:189], v[100:103]
	v_mfma_f32_16x16x32_bf16 v[84:87], v[158:161], v[198:201], v[84:87]
	v_mfma_f32_16x16x32_bf16 v[84:87], v[162:165], v[202:205], v[84:87]
	v_mfma_f32_16x16x32_bf16 v[80:83], v[166:169], v[198:201], v[80:83]
	v_mfma_f32_16x16x32_bf16 v[80:83], v[170:173], v[202:205], v[80:83]
	v_mfma_f32_16x16x32_bf16 v[64:67], v[166:169], v[206:209], v[64:67]
	v_mfma_f32_16x16x32_bf16 v[64:67], v[170:173], v[210:213], v[64:67]
	v_mfma_f32_16x16x32_bf16 v[68:71], v[158:161], v[206:209], v[68:71]
	v_mfma_f32_16x16x32_bf16 v[68:71], v[162:165], v[210:213], v[68:71]
	s_setprio 0
	s_barrier
	s_add_i32 s42, s59, s3
	v_lshl_add_u64 v[190:191], v[190:191], 0, s[8:9]
	s_mov_b32 m0, s42
	ds_read_b128 v[174:177], v197 offset:49152
	ds_read_b128 v[178:181], v197 offset:50176
	ds_read_b128 v[182:185], v197 offset:51200
	ds_read_b128 v[186:189], v197 offset:52224
	ds_read_b128 v[198:201], v197 offset:53248
	ds_read_b128 v[202:205], v197 offset:54272
	ds_read_b128 v[206:209], v197 offset:55296
	ds_read_b128 v[210:213], v197 offset:56320
	global_load_lds_dwordx4 v[190:191], off
	s_add_i32 m0, s42, 0x2000
	s_add_u32 s40, s40, 0x100080
	v_lshl_add_u64 v[190:191], v[214:215], 0, s[8:9]
	s_addc_u32 s41, s41, 0
	s_add_i32 s42, s62, s3
	global_load_lds_dwordx4 v[190:191], off
	v_lshl_add_u64 v[190:191], s[40:41], 0, v[128:129]
	s_mov_b32 m0, s42
	s_nop 0
	global_load_lds_dwordx4 v[190:191], off
	v_lshl_add_u64 v[190:191], s[40:41], 0, v[130:131]
	s_add_i32 m0, s42, 0x2000
	s_nop 0
	global_load_lds_dwordx4 v[190:191], off
	v_lshl_add_u64 v[190:191], v[216:217], 0, s[8:9]
	s_mov_b32 m0, s44
	s_nop 0
	global_load_lds_dwordx4 v[190:191], off
	v_lshl_add_u64 v[190:191], v[218:219], 0, s[8:9]
	s_mov_b32 m0, s45
	s_nop 0
	global_load_lds_dwordx4 v[190:191], off
	s_waitcnt vmcnt(8)
	s_waitcnt lgkmcnt(0)
	s_barrier
	s_setprio 1
	s_waitcnt lgkmcnt(0)
	v_mfma_f32_16x16x32_bf16 v[60:63], v[142:145], v[174:177], v[60:63]
	v_mfma_f32_16x16x32_bf16 v[60:63], v[146:149], v[178:181], v[60:63]
	v_mfma_f32_16x16x32_bf16 v[56:59], v[150:153], v[174:177], v[56:59]
	v_mfma_f32_16x16x32_bf16 v[56:59], v[154:157], v[178:181], v[56:59]
	v_mfma_f32_16x16x32_bf16 v[40:43], v[150:153], v[182:185], v[40:43]
	v_mfma_f32_16x16x32_bf16 v[40:43], v[154:157], v[186:189], v[40:43]
	v_mfma_f32_16x16x32_bf16 v[44:47], v[142:145], v[182:185], v[44:47]
	v_mfma_f32_16x16x32_bf16 v[44:47], v[146:149], v[186:189], v[44:47]
	v_mfma_f32_16x16x32_bf16 v[28:31], v[142:145], v[198:201], v[28:31]
	v_mfma_f32_16x16x32_bf16 v[28:31], v[146:149], v[202:205], v[28:31]
	v_mfma_f32_16x16x32_bf16 v[24:27], v[150:153], v[198:201], v[24:27]
	v_mfma_f32_16x16x32_bf16 v[24:27], v[154:157], v[202:205], v[24:27]
	v_mfma_f32_16x16x32_bf16 v[8:11], v[150:153], v[206:209], v[8:11]
	v_mfma_f32_16x16x32_bf16 v[8:11], v[154:157], v[210:213], v[8:11]
	v_mfma_f32_16x16x32_bf16 v[12:15], v[142:145], v[206:209], v[12:15]
	v_mfma_f32_16x16x32_bf16 v[12:15], v[146:149], v[210:213], v[12:15]
	s_setprio 0
	s_setprio 1
	v_mfma_f32_16x16x32_bf16 v[52:55], v[158:161], v[174:177], v[52:55]
	v_mfma_f32_16x16x32_bf16 v[52:55], v[162:165], v[178:181], v[52:55]
	v_mfma_f32_16x16x32_bf16 v[48:51], v[166:169], v[174:177], v[48:51]
	v_mfma_f32_16x16x32_bf16 v[48:51], v[170:173], v[178:181], v[48:51]
	v_mfma_f32_16x16x32_bf16 v[32:35], v[166:169], v[182:185], v[32:35]
	v_mfma_f32_16x16x32_bf16 v[32:35], v[170:173], v[186:189], v[32:35]
	v_mfma_f32_16x16x32_bf16 v[36:39], v[158:161], v[182:185], v[36:39]
	v_mfma_f32_16x16x32_bf16 v[36:39], v[162:165], v[186:189], v[36:39]
	v_mfma_f32_16x16x32_bf16 v[20:23], v[158:161], v[198:201], v[20:23]
	v_mfma_f32_16x16x32_bf16 v[20:23], v[162:165], v[202:205], v[20:23]
	v_mfma_f32_16x16x32_bf16 v[16:19], v[166:169], v[198:201], v[16:19]
	v_mfma_f32_16x16x32_bf16 v[16:19], v[170:173], v[202:205], v[16:19]
	v_mfma_f32_16x16x32_bf16 v[0:3], v[166:169], v[206:209], v[0:3]
	v_mfma_f32_16x16x32_bf16 v[0:3], v[170:173], v[210:213], v[0:3]
	v_mfma_f32_16x16x32_bf16 v[4:7], v[158:161], v[206:209], v[4:7]
	v_mfma_f32_16x16x32_bf16 v[4:7], v[162:165], v[210:213], v[4:7]
	s_setprio 0
	s_barrier
	s_add_i32 s58, s58, 2
	s_add_u32 s38, s38, 0x100
	s_addc_u32 s39, s39, 0
	s_add_u32 s56, s56, 0x100
	s_addc_u32 s57, s57, 0
	s_cmp_gt_u32 s58, 61
	s_cbranch_scc0 .LBB0_828
	s_and_b64 vcc, exec, s[10:11]
	s_cbranch_vccz .LBB0_831
	s_barrier
